# v9: v8 + P2 PV deep prefetch of transposed V fragment reads
# baseline (speedup 1.0000x reference)
; DI void attn0_phase(const unsigned char* QKV, bf16_t* OG, float* LSE, LAS unsigned char* lds, int tid, int bid, int G) {
;     ...
;         float mx = -__builtin_inff();
; #pragma unroll
;         for (int tt = 0; tt < 9; ++tt)
; #pragma unroll
;             for (int j = 0; j < 4; ++j) { const int kf = 16 * (w + tt) + 4 * g4 + j; const bool ok = (kf >= iq) && (kf <= iq + 128) && (nb > 0 || kf >= 128);
;                 const float xx = ok ? s[tt][j] : -__builtin_inff(); s[tt][j] = xx; mx = fmaxf(mx, xx); }
.LBB0_416:
	s_ashr_i32 s38, s89, 11
	s_lshl_b32 s14, s38, 1
	s_lshr_b32 s39, 64, s14
	s_bfe_u32 s0, s89, 0x60004
	s_sub_i32 s15, 6, s14
	s_add_i32 s39, s39, -1
	s_lshr_b32 s15, s0, s15
	s_and_b32 s39, s39, s0
	s_and_b32 s0, s37, 0x2000
	s_or_b32 s0, s15, s0
	v_lshl_add_u32 v10, s39, 7, v98
	s_and_b32 s89, s89, 15
	v_ashrrev_i32_e32 v11, 31, v10
	s_cmp_lg_u32 s39, 0
	v_readlane_b32 s40, v254, 31
	v_lshlrev_b64 v[10:11], s14, v[10:11]
	s_cselect_b64 s[14:15], -1, 0
	v_readlane_b32 s41, v254, 32
	s_or_b64 vcc, s[40:41], s[14:15]
	v_readlane_b32 s40, v254, 29
	v_readlane_b32 s41, v254, 30
	s_and_b64 vcc, s[40:41], vcc
	v_readlane_b32 s40, v254, 35
	v_readlane_b32 s41, v254, 36
	v_cndmask_b32_e32 v9, v125, v80, vcc
	s_or_b64 vcc, s[40:41], s[14:15]
	v_readlane_b32 s40, v254, 33
	v_readlane_b32 s41, v254, 34
	s_and_b64 vcc, s[40:41], vcc
	v_readlane_b32 s40, v254, 39
	v_readlane_b32 s41, v254, 40
	v_cndmask_b32_e32 v80, v125, v81, vcc
	s_or_b64 vcc, s[40:41], s[14:15]
	v_readlane_b32 s40, v254, 37
	v_readlane_b32 s41, v254, 38
	s_and_b64 vcc, s[40:41], vcc
	v_readlane_b32 s40, v254, 43
	v_readlane_b32 s41, v254, 44
	v_cndmask_b32_e32 v82, v125, v82, vcc
	s_or_b64 vcc, s[40:41], s[14:15]
	v_readlane_b32 s40, v254, 41
	v_readlane_b32 s41, v254, 42
	s_and_b64 vcc, s[40:41], vcc
	v_readlane_b32 s40, v254, 47
	v_readlane_b32 s41, v254, 48
	v_cndmask_b32_e32 v83, v125, v83, vcc
	s_or_b64 vcc, s[40:41], s[14:15]
	v_readlane_b32 s40, v254, 45
	v_readlane_b32 s41, v254, 46
	s_and_b64 vcc, s[40:41], vcc
	v_readlane_b32 s40, v254, 51
	v_readlane_b32 s41, v254, 52
	v_cndmask_b32_e32 v76, v125, v76, vcc
	s_or_b64 vcc, s[40:41], s[14:15]
	v_readlane_b32 s40, v254, 49
	v_readlane_b32 s41, v254, 50
	s_and_b64 vcc, s[40:41], vcc
	v_readlane_b32 s40, v254, 55
	v_readlane_b32 s41, v254, 56
	v_cndmask_b32_e32 v77, v125, v77, vcc
	s_or_b64 vcc, s[40:41], s[14:15]
	v_readlane_b32 s40, v254, 53
	v_readlane_b32 s41, v254, 54
	s_and_b64 vcc, s[40:41], vcc
	v_readlane_b32 s40, v254, 59
	v_readlane_b32 s41, v254, 60
	v_cndmask_b32_e32 v78, v125, v78, vcc
	s_or_b64 vcc, s[40:41], s[14:15]
	v_readlane_b32 s40, v254, 57
	v_readlane_b32 s41, v254, 58
	s_and_b64 vcc, s[40:41], vcc
	v_readlane_b32 s40, v254, 63
	v_readlane_b32 s41, v255, 0
	v_cndmask_b32_e32 v79, v125, v79, vcc
	s_or_b64 vcc, s[40:41], s[14:15]
	v_readlane_b32 s40, v254, 61
	v_readlane_b32 s41, v254, 62
	s_and_b64 vcc, s[40:41], vcc
	v_readlane_b32 s40, v255, 3
	v_readlane_b32 s41, v255, 4
	v_cndmask_b32_e32 v72, v125, v72, vcc
	s_or_b64 vcc, s[40:41], s[14:15]
	v_readlane_b32 s40, v255, 1
	v_readlane_b32 s41, v255, 2
	s_and_b64 vcc, s[40:41], vcc
	v_readlane_b32 s40, v255, 7
	v_readlane_b32 s41, v255, 8
	v_cndmask_b32_e32 v73, v125, v73, vcc
	s_or_b64 vcc, s[40:41], s[14:15]
	v_readlane_b32 s40, v255, 5
	v_readlane_b32 s41, v255, 6
	s_and_b64 vcc, s[40:41], vcc
	v_readlane_b32 s40, v255, 11
	v_readlane_b32 s41, v255, 12
	v_cndmask_b32_e32 v74, v125, v74, vcc
	s_or_b64 vcc, s[40:41], s[14:15]
	v_readlane_b32 s40, v255, 9
	v_readlane_b32 s41, v255, 10
	s_and_b64 vcc, s[40:41], vcc
	v_readlane_b32 s40, v255, 15
	v_readlane_b32 s41, v255, 16
	v_cndmask_b32_e32 v75, v125, v75, vcc
	s_or_b64 vcc, s[40:41], s[14:15]
	v_readlane_b32 s40, v255, 13
	v_readlane_b32 s41, v255, 14
	s_and_b64 vcc, s[40:41], vcc
	v_readlane_b32 s40, v255, 19
	v_readlane_b32 s41, v255, 20
	v_cndmask_b32_e32 v68, v125, v68, vcc
	s_or_b64 vcc, s[40:41], s[14:15]
	v_readlane_b32 s40, v255, 17
	v_readlane_b32 s41, v255, 18
	s_and_b64 vcc, s[40:41], vcc
	v_readlane_b32 s40, v255, 23
	v_readlane_b32 s41, v255, 24
	v_cndmask_b32_e32 v69, v125, v69, vcc
	s_or_b64 vcc, s[40:41], s[14:15]
	v_readlane_b32 s40, v255, 21
	v_readlane_b32 s41, v255, 22
	s_and_b64 vcc, s[40:41], vcc
	v_readlane_b32 s40, v255, 27
	v_readlane_b32 s41, v255, 28
	v_cndmask_b32_e32 v70, v125, v70, vcc
	s_or_b64 vcc, s[40:41], s[14:15]
	v_readlane_b32 s40, v255, 25
	v_readlane_b32 s41, v255, 26
	s_and_b64 vcc, s[40:41], vcc
	v_readlane_b32 s40, v255, 31
	v_readlane_b32 s41, v255, 32
	v_cndmask_b32_e32 v71, v125, v71, vcc
	s_or_b64 vcc, s[40:41], s[14:15]
	v_readlane_b32 s40, v255, 29
	v_readlane_b32 s41, v255, 30
	s_and_b64 vcc, s[40:41], vcc
	v_cndmask_b32_e32 v64, v125, v64, vcc
	s_or_b64 vcc, s[42:43], s[14:15]
	s_and_b64 vcc, s[4:5], vcc
	v_cndmask_b32_e32 v93, v125, v65, vcc
	s_or_b64 vcc, s[44:45], s[14:15]
	s_and_b64 vcc, s[16:17], vcc
	v_cndmask_b32_e32 v66, v125, v66, vcc
	s_or_b64 vcc, s[46:47], s[14:15]
	s_and_b64 vcc, s[2:3], vcc
	v_cndmask_b32_e32 v67, v125, v67, vcc
	s_or_b64 vcc, s[48:49], s[14:15]
	s_and_b64 vcc, s[18:19], vcc
	v_cndmask_b32_e32 v60, v125, v60, vcc
	s_or_b64 vcc, s[50:51], s[14:15]
	v_lshl_add_u64 v[10:11], v[10:11], 0, s[0:1]
	s_mov_b32 s0, 0xff800000
	s_and_b64 vcc, s[86:87], vcc
	v_max3_f32 v81, v9, s0, v80
	v_cndmask_b32_e32 v61, v125, v61, vcc
	s_or_b64 vcc, s[52:53], s[14:15]
	v_max3_f32 v81, v81, v82, v83
	s_and_b64 vcc, s[20:21], vcc
	v_max3_f32 v81, v81, v76, v77
	v_cndmask_b32_e32 v62, v125, v62, vcc
	s_or_b64 vcc, s[54:55], s[14:15]
	v_max3_f32 v81, v81, v78, v79
	s_and_b64 vcc, s[6:7], vcc
	v_max3_f32 v81, v81, v72, v73
	v_cndmask_b32_e32 v63, v125, v63, vcc
	s_or_b64 vcc, s[56:57], s[14:15]
	v_max3_f32 v81, v81, v74, v75
	s_and_b64 vcc, s[22:23], vcc
	v_max3_f32 v81, v81, v68, v69
	v_cndmask_b32_e32 v56, v125, v56, vcc
	s_or_b64 vcc, s[58:59], s[14:15]
	v_max3_f32 v81, v81, v70, v71
	s_and_b64 vcc, s[92:93], vcc
	v_max3_f32 v65, v81, v64, v93
	v_cndmask_b32_e32 v81, v125, v57, vcc
	s_or_b64 vcc, s[60:61], s[14:15]
	s_and_b64 vcc, s[24:25], vcc
	v_cndmask_b32_e32 v127, v125, v58, vcc
	s_or_b64 vcc, s[62:63], s[14:15]
; __device__ __forceinline__ unsigned cvt_pk_bf16(float lo, float hi) { unsigned r; asm volatile("v_cvt_pk_bf16_f32 %0, %1, %2" : "=v"(r) : "v"(lo), "v"(hi)); return r; }
; #define LAS __attribute__((address_space(3)))
; DI void attn0_phase(const unsigned char* QKV, bf16_t* OG, float* LSE, LAS unsigned char* lds, int tid, int bid, int G) {
;     ...
;         mx = fmaxf(mx, __shfl_xor(mx, 16)); mx = fmaxf(mx, __shfl_xor(mx, 32));
;         const float msc = mx * SM_C; float lsum = 0.f;
; #pragma unroll
;         for (int tt = 0; tt < 9; ++tt)
; #pragma unroll
;             for (int j = 0; j < 4; ++j) { const float p = __builtin_amdgcn_exp2f(s[tt][j] * SM_C - msc); s[tt][j] = p; lsum += p; }
;         lsum += __shfl_xor(lsum, 16); lsum += __shfl_xor(lsum, 32);
;         f32x4 o[8];
; #pragma unroll
;         for (int dt = 0; dt < 8; ++dt) o[dt] = (f32x4){0.f, 0.f, 0.f, 0.f};
; #pragma unroll
;         for (int kk = 0; kk < 5; ++kk) {
;             const int t0 = 2 * kk, t1 = 2 * kk + 1;
;             u32x4 pw; pw.x = pg8::cvt_pk_bf16(s[t0][0], s[t0][1]); pw.y = pg8::cvt_pk_bf16(s[t0][2], s[t0][3]);
;             if (t1 < 9) { pw.z = pg8::cvt_pk_bf16(s[t1 < 9 ? t1 : 8][0], s[t1 < 9 ? t1 : 8][1]); pw.w = pg8::cvt_pk_bf16(s[t1 < 9 ? t1 : 8][2], s[t1 < 9 ? t1 : 8][3]); } else { pw.z = 0u; pw.w = 0u; }
;             const bf16x8 pf = __builtin_bit_cast(bf16x8, pw);
;             int T1 = w + t1; T1 = T1 > 15 ? 15 : T1;
;             const int row0 = 16 * (w + t0) * 256, row1 = 16 * T1 * 256;
; #pragma unroll
;             for (int dt = 0; dt < 8; ++dt) {
;                 const int choff = ((2 * dt + (p4 >> 1)) ^ (2 * q4)) * 16;
;                 const s16x4 lo = __builtin_amdgcn_ds_read_tr16_b64_v4i16((LAS s16x4*)(vt + tr_base + row0 + choff));
;                 const s16x4 hi = __builtin_amdgcn_ds_read_tr16_b64_v4i16((LAS s16x4*)(vt + tr_base + row1 + choff));
;                 const bf16x8 vf = __builtin_shufflevector(lo, hi, 0, 1, 2, 3, 4, 5, 6, 7);
;                 o[dt] = __builtin_amdgcn_mfma_f32_16x16x32_bf16(vf, pf, o[dt], 0, 0, 0); }
	s_and_b64 vcc, s[8:9], vcc
	v_cndmask_b32_e32 v128, v125, v59, vcc
	s_or_b64 vcc, s[64:65], s[14:15]
	s_and_b64 vcc, s[26:27], vcc
	v_cndmask_b32_e32 v129, v125, v52, vcc
	s_or_b64 vcc, s[66:67], s[14:15]
	s_and_b64 vcc, s[90:91], vcc
	v_cndmask_b32_e32 v130, v125, v53, vcc
	s_or_b64 vcc, s[68:69], s[14:15]
	s_and_b64 vcc, s[28:29], vcc
	v_cndmask_b32_e32 v54, v125, v54, vcc
	s_or_b64 vcc, s[70:71], s[14:15]
	s_and_b64 vcc, s[10:11], vcc
	v_max3_f32 v65, v65, v66, v67
	v_cndmask_b32_e32 v55, v125, v55, vcc
	s_or_b64 vcc, s[72:73], s[14:15]
	v_max3_f32 v65, v65, v60, v61
	s_and_b64 vcc, s[30:31], vcc
	v_max3_f32 v65, v65, v62, v63
	v_cndmask_b32_e32 v131, v125, v84, vcc
	s_or_b64 vcc, s[74:75], s[14:15]
	v_max3_f32 v57, v65, v56, v81
	s_and_b64 vcc, s[96:97], vcc
	v_max3_f32 v57, v57, v127, v128
	v_cndmask_b32_e32 v132, v125, v85, vcc
	s_or_b64 vcc, s[76:77], s[14:15]
	v_max3_f32 v52, v57, v129, v130
	s_and_b64 vcc, s[34:35], vcc
	s_or_b64 s[14:15], s[78:79], s[14:15]
	v_and_b32_e32 v57, 64, v124
	v_cndmask_b32_e32 v86, v125, v86, vcc
	s_and_b64 vcc, s[12:13], s[14:15]
	v_xor_b32_e32 v53, 16, v124
	v_add_u32_e32 v57, 64, v57
	v_max3_f32 v52, v52, v54, v55
	v_cndmask_b32_e32 v84, v125, v87, vcc
	v_cmp_lt_i32_e32 vcc, v53, v57
	v_max3_f32 v52, v52, v131, v132
	v_max3_f32 v52, v52, v86, v84
	v_cndmask_b32_e32 v53, v124, v53, vcc
	v_lshlrev_b32_e32 v87, 2, v53
	ds_bpermute_b32 v53, v87, v52
	s_ashr_i32 s39, s38, 31
	v_readlane_b32 s0, v254, 21
	v_readlane_b32 s40, v254, 27
	v_readlane_b32 s41, v254, 28
	s_waitcnt lgkmcnt(0)
	v_max_f32_e32 v53, v53, v53
	v_max_f32_e32 v52, v52, v53
	v_xor_b32_e32 v53, 32, v124
	v_cmp_lt_i32_e32 vcc, v53, v57
	s_nop 1
	v_cndmask_b32_e32 v53, v124, v53, vcc
	v_lshlrev_b32_e32 v133, 2, v53
	ds_bpermute_b32 v53, v133, v52
	s_waitcnt lgkmcnt(0)
	v_max_f32_e32 v53, v53, v53
	v_max_f32_e32 v85, v52, v53
	v_pk_mul_f32 v[52:53], v[84:85], s[36:37] op_sel_hi:[1,0]
	s_nop 0
	v_fma_f32 v9, v9, s36, -v53
	v_exp_f32_e32 v134, v9
	v_fma_f32 v57, v80, s36, -v53
	v_exp_f32_e32 v80, v57
	v_fma_f32 v57, v82, s36, -v53
	v_exp_f32_e32 v82, v57
	v_fma_f32 v57, v83, s36, -v53
	v_exp_f32_e32 v83, v57
	v_fma_f32 v57, v76, s36, -v53
	v_add_f32_e32 v9, 0, v134
	v_exp_f32_e32 v76, v57
	v_fma_f32 v57, v77, s36, -v53
	v_add_f32_e32 v9, v80, v9
	v_exp_f32_e32 v77, v57
	v_fma_f32 v57, v78, s36, -v53
	v_add_f32_e32 v9, v82, v9
	v_exp_f32_e32 v78, v57
	v_fma_f32 v57, v79, s36, -v53
	v_add_f32_e32 v9, v83, v9
	v_exp_f32_e32 v79, v57
	v_fma_f32 v57, v72, s36, -v53
	v_add_f32_e32 v9, v76, v9
	v_exp_f32_e32 v148, v57
	v_fma_f32 v57, v73, s36, -v53
	v_add_f32_e32 v9, v77, v9
	v_exp_f32_e32 v149, v57
	v_fma_f32 v57, v74, s36, -v53
	v_add_f32_e32 v9, v78, v9
	v_exp_f32_e32 v150, v57
	v_fma_f32 v57, v75, s36, -v53
	v_add_f32_e32 v9, v79, v9
	v_exp_f32_e32 v151, v57
	v_fma_f32 v57, v68, s36, -v53
	v_add_f32_e32 v9, v148, v9
	v_exp_f32_e32 v152, v57
	v_fma_f32 v57, v69, s36, -v53
	v_add_f32_e32 v9, v149, v9
	v_exp_f32_e32 v153, v57
	v_fma_f32 v57, v70, s36, -v53
	v_add_f32_e32 v9, v150, v9
	v_exp_f32_e32 v154, v57
	v_fma_f32 v57, v71, s36, -v53
	v_add_f32_e32 v9, v151, v9
	v_exp_f32_e32 v155, v57
	v_fma_f32 v57, v64, s36, -v53
	v_add_f32_e32 v9, v152, v9
	v_exp_f32_e32 v65, v57
	v_fma_f32 v57, v93, s36, -v53
	v_add_f32_e32 v9, v153, v9
	v_exp_f32_e32 v93, v57
	v_fma_f32 v57, v66, s36, -v53
	v_add_f32_e32 v9, v154, v9
	v_exp_f32_e32 v156, v57
	v_fma_f32 v57, v67, s36, -v53
	v_add_f32_e32 v9, v155, v9
	v_exp_f32_e32 v157, v57
	v_fma_f32 v57, v60, s36, -v53
	v_add_f32_e32 v9, v65, v9
	v_exp_f32_e32 v158, v57
	v_fma_f32 v57, v61, s36, -v53
	v_add_f32_e32 v9, v93, v9
	v_exp_f32_e32 v159, v57
	v_fma_f32 v57, v62, s36, -v53
	v_add_f32_e32 v9, v156, v9
	v_exp_f32_e32 v160, v57
	v_fma_f32 v57, v63, s36, -v53
	v_add_f32_e32 v9, v157, v9
	v_exp_f32_e32 v161, v57
	v_fma_f32 v56, v56, s36, -v53
	v_add_f32_e32 v9, v158, v9
	v_exp_f32_e32 v57, v56
	v_fma_f32 v56, v81, s36, -v53
	v_add_f32_e32 v9, v159, v9
	v_exp_f32_e32 v58, v56
	v_fma_f32 v56, v127, s36, -v53
	v_add_f32_e32 v9, v160, v9
	v_exp_f32_e32 v59, v56
	v_fma_f32 v56, v128, s36, -v53
	v_add_f32_e32 v9, v161, v9
	v_exp_f32_e32 v60, v56
	v_fma_f32 v56, v129, s36, -v53
	v_add_f32_e32 v9, v57, v9
	v_exp_f32_e32 v61, v56
	v_fma_f32 v56, v130, s36, -v53
	v_add_f32_e32 v9, v58, v9
	v_exp_f32_e32 v62, v56
	v_fma_f32 v54, v54, s36, -v53
	v_add_f32_e32 v9, v59, v9
	v_exp_f32_e32 v63, v54
	v_fma_f32 v54, v55, s36, -v53
	v_add_f32_e32 v9, v60, v9
	v_exp_f32_e32 v64, v54
	v_fma_f32 v54, v131, s36, -v53
	v_add_f32_e32 v9, v61, v9
	v_exp_f32_e32 v54, v54
	v_fma_f32 v55, v132, s36, -v53
	v_add_f32_e32 v9, v62, v9
	v_exp_f32_e32 v55, v55
	v_fma_f32 v56, v86, s36, -v53
	v_add_f32_e32 v9, v63, v9
	v_exp_f32_e32 v56, v56
	v_sub_f32_e32 v52, v52, v53
	v_add_f32_e32 v9, v64, v9
	v_exp_f32_e32 v52, v52
	v_add_f32_e32 v9, v54, v9
	v_add_f32_e32 v9, v55, v9
	v_add_f32_e32 v9, v56, v9
	v_add_f32_e32 v9, v52, v9
	ds_bpermute_b32 v53, v87, v9
	v_cvt_pk_bf16_f32 v66, v134, v80
	v_cvt_pk_bf16_f32 v67, v82, v83
	s_waitcnt lgkmcnt(0)
	v_add_f32_e32 v9, v9, v53
	v_cvt_pk_bf16_f32 v68, v76, v77
	v_cvt_pk_bf16_f32 v69, v78, v79
	ds_bpermute_b32 v84, v133, v9
	v_add_u32_e32 v226, v100, v99
	ds_read_b64_tr_b16 v[162:163], v226
	v_add_u32_e32 v227, v101, v99
	ds_read_b64_tr_b16 v[164:165], v227
	v_add_u32_e32 v226, v100, v102
	ds_read_b64_tr_b16 v[166:167], v226
	v_add_u32_e32 v227, v101, v102
	ds_read_b64_tr_b16 v[168:169], v227
	v_add_u32_e32 v226, v100, v103
	ds_read_b64_tr_b16 v[170:171], v226
	v_add_u32_e32 v227, v101, v103
	ds_read_b64_tr_b16 v[172:173], v227
	v_add_u32_e32 v226, v100, v104
	ds_read_b64_tr_b16 v[174:175], v226
	v_add_u32_e32 v227, v101, v104
	ds_read_b64_tr_b16 v[176:177], v227
	v_add_u32_e32 v226, v100, v99
	ds_read_b64_tr_b16 v[178:179], v226 offset:128
	v_add_u32_e32 v227, v101, v99
	ds_read_b64_tr_b16 v[180:181], v227 offset:128
	v_add_u32_e32 v226, v100, v105
	ds_read_b64_tr_b16 v[182:183], v226
	v_add_u32_e32 v227, v101, v105
	ds_read_b64_tr_b16 v[184:185], v227
	v_add_u32_e32 v226, v100, v106
	ds_read_b64_tr_b16 v[186:187], v226
	v_add_u32_e32 v227, v101, v106
	ds_read_b64_tr_b16 v[188:189], v227
	s_waitcnt lgkmcnt(12)
; __device__ __forceinline__ unsigned cvt_pk_bf16(float lo, float hi) { unsigned r; asm volatile("v_cvt_pk_bf16_f32 %0, %1, %2" : "=v"(r) : "v"(lo), "v"(hi)); return r; }
; #define LAS __attribute__((address_space(3)))
; DI void attn0_phase(const unsigned char* QKV, bf16_t* OG, float* LSE, LAS unsigned char* lds, int tid, int bid, int G) {
;     ...
; #pragma unroll
;         for (int kk = 0; kk < 5; ++kk) {
;             const int t0 = 2 * kk, t1 = 2 * kk + 1;
;             u32x4 pw; pw.x = pg8::cvt_pk_bf16(s[t0][0], s[t0][1]); pw.y = pg8::cvt_pk_bf16(s[t0][2], s[t0][3]);
;             if (t1 < 9) { pw.z = pg8::cvt_pk_bf16(s[t1 < 9 ? t1 : 8][0], s[t1 < 9 ? t1 : 8][1]); pw.w = pg8::cvt_pk_bf16(s[t1 < 9 ? t1 : 8][2], s[t1 < 9 ? t1 : 8][3]); } else { pw.z = 0u; pw.w = 0u; }
;             const bf16x8 pf = __builtin_bit_cast(bf16x8, pw);
;             int T1 = w + t1; T1 = T1 > 15 ? 15 : T1;
;             const int row0 = 16 * (w + t0) * 256, row1 = 16 * T1 * 256;
; #pragma unroll
;             for (int dt = 0; dt < 8; ++dt) {
;                 const int choff = ((2 * dt + (p4 >> 1)) ^ (2 * q4)) * 16;
;                 const s16x4 lo = __builtin_amdgcn_ds_read_tr16_b64_v4i16((LAS s16x4*)(vt + tr_base + row0 + choff));
;                 const s16x4 hi = __builtin_amdgcn_ds_read_tr16_b64_v4i16((LAS s16x4*)(vt + tr_base + row1 + choff));
;                 const bf16x8 vf = __builtin_shufflevector(lo, hi, 0, 1, 2, 3, 4, 5, 6, 7);
;                 o[dt] = __builtin_amdgcn_mfma_f32_16x16x32_bf16(vf, pf, o[dt], 0, 0, 0); }
	v_mfma_f32_16x16x32_bf16 v[70:73], v[162:165], v[66:69], 0
	v_add_u32_e32 v226, v100, v107
	ds_read_b64_tr_b16 v[162:163], v226
	v_add_u32_e32 v227, v101, v107
	ds_read_b64_tr_b16 v[164:165], v227
	v_add_f32_e32 v9, v9, v84
	v_div_scale_f32 v84, s[14:15], v9, v9, 1.0
	s_waitcnt lgkmcnt(12)
	s_nop 0
	v_mfma_f32_16x16x32_bf16 v[74:77], v[166:169], v[66:69], 0
	v_add_u32_e32 v226, v108, v99
	ds_read_b64_tr_b16 v[166:167], v226
	v_add_u32_e32 v227, v109, v99
	ds_read_b64_tr_b16 v[168:169], v227
	v_rcp_f32_e32 v86, v84
	s_lshl_b64 s[14:15], s[38:39], 26
	s_add_u32 s14, s0, s14
	s_waitcnt lgkmcnt(12)
	v_mfma_f32_16x16x32_bf16 v[78:81], v[170:173], v[66:69], 0
	v_add_u32_e32 v226, v108, v102
	ds_read_b64_tr_b16 v[170:171], v226
	v_add_u32_e32 v227, v109, v102
	ds_read_b64_tr_b16 v[172:173], v227
	v_fma_f32 v87, -v84, v86, 1.0
	v_fmac_f32_e32 v86, v87, v86
	v_div_scale_f32 v87, vcc, 1.0, v9, 1.0
	s_waitcnt lgkmcnt(12)
	s_nop 0
	v_mfma_f32_16x16x32_bf16 v[128:131], v[174:177], v[66:69], 0
	v_add_u32_e32 v226, v108, v103
	ds_read_b64_tr_b16 v[174:175], v226
	v_add_u32_e32 v227, v109, v103
	ds_read_b64_tr_b16 v[176:177], v227
	v_readlane_b32 s0, v254, 22
	s_addc_u32 s15, s0, s15
	s_lshl_b32 s0, s89, 8
	s_waitcnt lgkmcnt(12)
	v_mfma_f32_16x16x32_bf16 v[132:135], v[178:181], v[66:69], 0
	v_add_u32_e32 v226, v108, v104
	ds_read_b64_tr_b16 v[178:179], v226
	v_add_u32_e32 v227, v109, v104
	ds_read_b64_tr_b16 v[180:181], v227
	s_waitcnt lgkmcnt(12)
	v_mfma_f32_16x16x32_bf16 v[136:139], v[182:185], v[66:69], 0
	v_add_u32_e32 v226, v108, v99
	ds_read_b64_tr_b16 v[182:183], v226 offset:128
	v_add_u32_e32 v227, v109, v99
	ds_read_b64_tr_b16 v[184:185], v227 offset:128
	s_waitcnt lgkmcnt(12)
	v_mfma_f32_16x16x32_bf16 v[140:143], v[186:189], v[66:69], 0
	v_add_u32_e32 v226, v108, v105
	ds_read_b64_tr_b16 v[186:187], v226
	v_add_u32_e32 v227, v109, v105
	ds_read_b64_tr_b16 v[188:189], v227
	s_waitcnt lgkmcnt(12)
	v_mfma_f32_16x16x32_bf16 v[66:69], v[162:165], v[66:69], 0
	v_add_u32_e32 v226, v108, v106
	ds_read_b64_tr_b16 v[162:163], v226
	v_add_u32_e32 v227, v109, v106
	ds_read_b64_tr_b16 v[164:165], v227
	v_cvt_pk_bf16_f32 v144, v148, v149
	v_cvt_pk_bf16_f32 v145, v150, v151
	v_cvt_pk_bf16_f32 v146, v152, v153
	v_cvt_pk_bf16_f32 v147, v154, v155
	s_waitcnt lgkmcnt(12)
	s_nop 0
	v_mfma_f32_16x16x32_bf16 v[70:73], v[166:169], v[144:147], v[70:73]
	v_add_u32_e32 v226, v108, v107
	ds_read_b64_tr_b16 v[166:167], v226
	v_add_u32_e32 v227, v109, v107
	ds_read_b64_tr_b16 v[168:169], v227
	s_waitcnt lgkmcnt(12)
	v_mfma_f32_16x16x32_bf16 v[74:77], v[170:173], v[144:147], v[74:77]
	v_add_u32_e32 v226, v110, v99
	ds_read_b64_tr_b16 v[170:171], v226
	v_add_u32_e32 v227, v111, v99
	ds_read_b64_tr_b16 v[172:173], v227
	s_waitcnt lgkmcnt(12)
	v_mfma_f32_16x16x32_bf16 v[78:81], v[174:177], v[144:147], v[78:81]
	v_add_u32_e32 v226, v110, v102
	ds_read_b64_tr_b16 v[174:175], v226
	v_add_u32_e32 v227, v111, v102
	ds_read_b64_tr_b16 v[176:177], v227
	s_waitcnt lgkmcnt(12)
	v_mfma_f32_16x16x32_bf16 v[128:131], v[178:181], v[144:147], v[128:131]
	v_add_u32_e32 v226, v110, v103
	ds_read_b64_tr_b16 v[178:179], v226
	v_add_u32_e32 v227, v111, v103
	ds_read_b64_tr_b16 v[180:181], v227
	s_waitcnt lgkmcnt(12)
	v_mfma_f32_16x16x32_bf16 v[132:135], v[182:185], v[144:147], v[132:135]
	v_add_u32_e32 v226, v110, v104
	ds_read_b64_tr_b16 v[182:183], v226
	v_add_u32_e32 v227, v111, v104
	ds_read_b64_tr_b16 v[184:185], v227
	s_waitcnt lgkmcnt(12)
	v_mfma_f32_16x16x32_bf16 v[136:139], v[186:189], v[144:147], v[136:139]
	v_add_u32_e32 v226, v110, v99
	ds_read_b64_tr_b16 v[186:187], v226 offset:128
	v_add_u32_e32 v227, v111, v99
	ds_read_b64_tr_b16 v[188:189], v227 offset:128
	s_waitcnt lgkmcnt(12)
	v_mfma_f32_16x16x32_bf16 v[140:143], v[162:165], v[144:147], v[140:143]
	v_add_u32_e32 v226, v110, v105
	ds_read_b64_tr_b16 v[162:163], v226
	v_add_u32_e32 v227, v111, v105
	ds_read_b64_tr_b16 v[164:165], v227
	s_waitcnt lgkmcnt(12)
	v_mfma_f32_16x16x32_bf16 v[66:69], v[166:169], v[144:147], v[66:69]
	v_add_u32_e32 v226, v110, v106
	ds_read_b64_tr_b16 v[166:167], v226
	v_add_u32_e32 v227, v111, v106
	ds_read_b64_tr_b16 v[168:169], v227
	v_cvt_pk_bf16_f32 v144, v65, v93
	v_cvt_pk_bf16_f32 v145, v156, v157
	v_cvt_pk_bf16_f32 v146, v158, v159
	v_cvt_pk_bf16_f32 v147, v160, v161
	s_waitcnt lgkmcnt(12)
	s_nop 0
	v_mfma_f32_16x16x32_bf16 v[70:73], v[170:173], v[144:147], v[70:73]
	v_add_u32_e32 v226, v112, v99
	ds_read_b64_tr_b16 v[170:171], v226
	v_add_u32_e32 v227, v113, v99
	ds_read_b64_tr_b16 v[172:173], v227
	s_waitcnt lgkmcnt(12)
	v_mfma_f32_16x16x32_bf16 v[74:77], v[174:177], v[144:147], v[74:77]
	v_add_u32_e32 v226, v112, v102
	ds_read_b64_tr_b16 v[174:175], v226
	v_add_u32_e32 v227, v113, v102
	ds_read_b64_tr_b16 v[176:177], v227
	s_waitcnt lgkmcnt(12)
	v_mfma_f32_16x16x32_bf16 v[78:81], v[178:181], v[144:147], v[78:81]
	v_add_u32_e32 v226, v110, v107
	ds_read_b64_tr_b16 v[178:179], v226
	v_add_u32_e32 v227, v111, v107
	ds_read_b64_tr_b16 v[180:181], v227
	s_waitcnt lgkmcnt(12)
	v_mfma_f32_16x16x32_bf16 v[128:131], v[182:185], v[144:147], v[128:131]
	v_add_u32_e32 v226, v112, v103
	ds_read_b64_tr_b16 v[182:183], v226
	v_add_u32_e32 v227, v113, v103
	ds_read_b64_tr_b16 v[184:185], v227
	v_mov_b32_e32 v154, v8
	s_waitcnt lgkmcnt(12)
	s_nop 0
	v_mfma_f32_16x16x32_bf16 v[132:135], v[186:189], v[144:147], v[132:135]
	v_add_u32_e32 v226, v112, v104
	ds_read_b64_tr_b16 v[186:187], v226
	v_add_u32_e32 v227, v113, v104
	ds_read_b64_tr_b16 v[188:189], v227
	s_waitcnt lgkmcnt(12)
	v_mfma_f32_16x16x32_bf16 v[136:139], v[162:165], v[144:147], v[136:139]
	v_add_u32_e32 v226, v112, v99
	ds_read_b64_tr_b16 v[162:163], v226 offset:128
	v_add_u32_e32 v227, v113, v99
	ds_read_b64_tr_b16 v[164:165], v227 offset:128
	s_waitcnt lgkmcnt(12)
; __device__ __forceinline__ unsigned cvt_pk_bf16(float lo, float hi) { unsigned r; asm volatile("v_cvt_pk_bf16_f32 %0, %1, %2" : "=v"(r) : "v"(lo), "v"(hi)); return r; }
; #define LAS __attribute__((address_space(3)))
; DI void attn0_phase(const unsigned char* QKV, bf16_t* OG, float* LSE, LAS unsigned char* lds, int tid, int bid, int G) {
;     ...
; #pragma unroll
;         for (int kk = 0; kk < 5; ++kk) {
;             const int t0 = 2 * kk, t1 = 2 * kk + 1;
;             u32x4 pw; pw.x = pg8::cvt_pk_bf16(s[t0][0], s[t0][1]); pw.y = pg8::cvt_pk_bf16(s[t0][2], s[t0][3]);
;             if (t1 < 9) { pw.z = pg8::cvt_pk_bf16(s[t1 < 9 ? t1 : 8][0], s[t1 < 9 ? t1 : 8][1]); pw.w = pg8::cvt_pk_bf16(s[t1 < 9 ? t1 : 8][2], s[t1 < 9 ? t1 : 8][3]); } else { pw.z = 0u; pw.w = 0u; }
;             const bf16x8 pf = __builtin_bit_cast(bf16x8, pw);
;             int T1 = w + t1; T1 = T1 > 15 ? 15 : T1;
;             const int row0 = 16 * (w + t0) * 256, row1 = 16 * T1 * 256;
; #pragma unroll
;             for (int dt = 0; dt < 8; ++dt) {
;                 const int choff = ((2 * dt + (p4 >> 1)) ^ (2 * q4)) * 16;
;                 const s16x4 lo = __builtin_amdgcn_ds_read_tr16_b64_v4i16((LAS s16x4*)(vt + tr_base + row0 + choff));
;                 const s16x4 hi = __builtin_amdgcn_ds_read_tr16_b64_v4i16((LAS s16x4*)(vt + tr_base + row1 + choff));
;                 const bf16x8 vf = __builtin_shufflevector(lo, hi, 0, 1, 2, 3, 4, 5, 6, 7);
;                 o[dt] = __builtin_amdgcn_mfma_f32_16x16x32_bf16(vf, pf, o[dt], 0, 0, 0); }
;         }
;         const float inv = 1.0f / lsum;
;         bf16_t* op = OG + (size_t)grp * GS + qtok * 2048 + h * 128 + 4 * g4;
; #pragma unroll
;         for (int dt = 0; dt < 8; ++dt) { u32x2 wv; wv.x = pg8::cvt_pk_bf16(o[dt][0] * inv, o[dt][1] * inv); wv.y = pg8::cvt_pk_bf16(o[dt][2] * inv, o[dt][3] * inv); *(u32x2*)(op + 16 * dt) = wv; }
;         if (g4 == 0) LSE[(size_t)grp * (MTOK * 16) + qtok * 16 + h] = mx * SM_SCALE + __logf(lsum);
	v_mfma_f32_16x16x32_bf16 v[140:143], v[166:169], v[144:147], v[140:143]
	v_add_u32_e32 v226, v112, v105
	ds_read_b64_tr_b16 v[166:167], v226
	v_add_u32_e32 v227, v113, v105
	ds_read_b64_tr_b16 v[168:169], v227
	v_cvt_pk_bf16_f32 v58, v57, v58
	v_cvt_pk_bf16_f32 v59, v59, v60
	v_cvt_pk_bf16_f32 v60, v61, v62
	v_cvt_pk_bf16_f32 v61, v63, v64
	s_waitcnt lgkmcnt(12)
	s_nop 0
	v_mfma_f32_16x16x32_bf16 v[62:65], v[170:173], v[58:61], v[70:73]
	v_add_u32_e32 v226, v112, v106
	ds_read_b64_tr_b16 v[170:171], v226
	v_add_u32_e32 v227, v113, v106
	ds_read_b64_tr_b16 v[172:173], v227
	s_nop 2
	s_waitcnt lgkmcnt(12)
	v_mfma_f32_16x16x32_bf16 v[70:73], v[174:177], v[58:61], v[74:77]
	v_add_u32_e32 v226, v114, v99
	ds_read_b64_tr_b16 v[174:175], v226
	v_add_u32_e32 v227, v115, v99
	ds_read_b64_tr_b16 v[176:177], v227 offset:36864
	s_nop 2
	s_waitcnt lgkmcnt(12)
	v_mfma_f32_16x16x32_bf16 v[66:69], v[178:181], v[144:147], v[66:69]
	v_add_u32_e32 v226, v112, v107
	ds_read_b64_tr_b16 v[178:179], v226
	v_add_u32_e32 v227, v113, v107
	ds_read_b64_tr_b16 v[180:181], v227
	v_mov_b32_e32 v155, v8
	v_mul_f32_e32 v93, v87, v86
	v_fma_f32 v127, -v84, v93, v87
	s_waitcnt lgkmcnt(12)
	s_nop 0
	v_mfma_f32_16x16x32_bf16 v[144:147], v[182:185], v[58:61], v[78:81]
	v_add_u32_e32 v226, v114, v102
	ds_read_b64_tr_b16 v[182:183], v226
	v_add_u32_e32 v227, v115, v102
	ds_read_b64_tr_b16 v[184:185], v227 offset:36864
	s_waitcnt lgkmcnt(12)
	v_mfma_f32_16x16x32_bf16 v[128:131], v[186:189], v[58:61], v[128:131]
	v_add_u32_e32 v226, v114, v103
	ds_read_b64_tr_b16 v[186:187], v226
	v_add_u32_e32 v227, v115, v103
	ds_read_b64_tr_b16 v[188:189], v227 offset:36864
	s_waitcnt lgkmcnt(12)
	v_mfma_f32_16x16x32_bf16 v[132:135], v[162:165], v[58:61], v[132:135]
	v_add_u32_e32 v226, v114, v104
	ds_read_b64_tr_b16 v[162:163], v226
	v_add_u32_e32 v227, v115, v104
	ds_read_b64_tr_b16 v[164:165], v227 offset:36864
	s_waitcnt lgkmcnt(12)
	v_mfma_f32_16x16x32_bf16 v[136:139], v[166:169], v[58:61], v[136:139]
	v_add_u32_e32 v226, v114, v99
	ds_read_b64_tr_b16 v[166:167], v226 offset:128
	v_add_u32_e32 v227, v115, v99
	ds_read_b64_tr_b16 v[168:169], v227 offset:36992
	s_waitcnt lgkmcnt(12)
	v_mfma_f32_16x16x32_bf16 v[140:143], v[170:173], v[58:61], v[140:143]
	v_add_u32_e32 v226, v114, v105
	ds_read_b64_tr_b16 v[170:171], v226
	v_add_u32_e32 v227, v115, v105
	ds_read_b64_tr_b16 v[172:173], v227 offset:36864
	v_cvt_pk_bf16_f32 v152, v54, v55
	v_cvt_pk_bf16_f32 v153, v56, v52
	s_waitcnt lgkmcnt(12)
	s_nop 0
	v_mfma_f32_16x16x32_bf16 v[80:83], v[174:177], v[152:155], v[62:65]
	v_add_u32_e32 v226, v114, v106
	ds_read_b64_tr_b16 v[174:175], v226
	v_add_u32_e32 v227, v115, v106
	ds_read_b64_tr_b16 v[176:177], v227 offset:36864
	s_waitcnt lgkmcnt(12)
	v_mfma_f32_16x16x32_bf16 v[148:151], v[178:181], v[58:61], v[66:69]
	v_add_u32_e32 v226, v114, v107
	ds_read_b64_tr_b16 v[178:179], v226
	v_add_u32_e32 v227, v115, v107
	ds_read_b64_tr_b16 v[180:181], v227 offset:36864
	v_fmac_f32_e32 v93, v127, v86
	v_fma_f32 v84, -v84, v93, v87
	v_div_fmas_f32 v84, v84, v86, v93
	s_waitcnt lgkmcnt(12)
	s_nop 0
	v_mfma_f32_16x16x32_bf16 v[76:79], v[182:185], v[152:155], v[70:73]
	s_waitcnt lgkmcnt(10)
	v_mfma_f32_16x16x32_bf16 v[72:75], v[186:189], v[152:155], v[144:147]
	s_waitcnt lgkmcnt(8)
	v_mfma_f32_16x16x32_bf16 v[68:71], v[162:165], v[152:155], v[128:131]
	v_lshlrev_b64 v[86:87], 12, v[10:11]
	v_div_fixup_f32 v84, v84, v9, 1.0
	s_waitcnt lgkmcnt(6)
	s_nop 0
	v_mfma_f32_16x16x32_bf16 v[64:67], v[166:169], v[152:155], v[132:135]
	s_waitcnt lgkmcnt(4)
	v_mfma_f32_16x16x32_bf16 v[60:63], v[170:173], v[152:155], v[136:139]
	s_waitcnt lgkmcnt(2)
	v_mfma_f32_16x16x32_bf16 v[56:59], v[174:177], v[152:155], v[140:143]
	v_lshl_add_u64 v[86:87], s[14:15], 0, v[86:87]
	v_lshl_add_u64 v[86:87], v[86:87], 0, s[0:1]
	v_mov_b32_e32 v93, v8
	v_mul_f32_e32 v80, v84, v80
	v_mul_f32_e32 v81, v84, v81
	v_lshl_add_u64 v[86:87], v[86:87], 0, v[92:93]
	v_cvt_pk_bf16_f32 v80, v80, v81
	v_mul_f32_e32 v81, v84, v82
	v_mul_f32_e32 v76, v84, v76
	v_mul_f32_e32 v77, v84, v77
	v_mul_f32_e32 v82, v84, v83
	v_cvt_pk_bf16_f32 v81, v81, v82
	global_store_dwordx2 v[86:87], v[80:81], off
	v_cvt_pk_bf16_f32 v76, v76, v77
	v_mul_f32_e32 v77, v84, v78
	v_mul_f32_e32 v72, v84, v72
	v_mul_f32_e32 v73, v84, v73
	s_waitcnt lgkmcnt(0)
	s_nop 0
	v_mfma_f32_16x16x32_bf16 v[52:55], v[178:181], v[152:155], v[148:151]
	v_mul_f32_e32 v78, v84, v79
	v_cvt_pk_bf16_f32 v77, v77, v78
	global_store_dwordx2 v[86:87], v[76:77], off offset:32
	v_cvt_pk_bf16_f32 v72, v72, v73
	v_mul_f32_e32 v73, v84, v74
	v_mul_f32_e32 v68, v84, v68
	v_mul_f32_e32 v69, v84, v69
	v_mul_f32_e32 v74, v84, v75
	v_cvt_pk_bf16_f32 v73, v73, v74
	global_store_dwordx2 v[86:87], v[72:73], off offset:64
	v_cvt_pk_bf16_f32 v68, v68, v69
	v_mul_f32_e32 v69, v84, v70
	v_mul_f32_e32 v64, v84, v64
	v_mul_f32_e32 v65, v84, v65
	v_mul_f32_e32 v70, v84, v71
	v_cvt_pk_bf16_f32 v69, v69, v70
	global_store_dwordx2 v[86:87], v[68:69], off offset:96
	v_cvt_pk_bf16_f32 v64, v64, v65
	v_mul_f32_e32 v65, v84, v66
	v_mul_f32_e32 v60, v84, v60
	v_mul_f32_e32 v61, v84, v61
	v_mul_f32_e32 v66, v84, v67
	v_cvt_pk_bf16_f32 v65, v65, v66
	global_store_dwordx2 v[86:87], v[64:65], off offset:128
	v_cvt_pk_bf16_f32 v60, v60, v61
	v_mul_f32_e32 v61, v84, v62
	v_mul_f32_e32 v56, v84, v56
	v_mul_f32_e32 v57, v84, v57
	v_mul_f32_e32 v62, v84, v63
	v_cvt_pk_bf16_f32 v61, v61, v62
	global_store_dwordx2 v[86:87], v[60:61], off offset:160
	v_cvt_pk_bf16_f32 v56, v56, v57
	v_mul_f32_e32 v57, v84, v58
	v_mul_f32_e32 v52, v84, v52
	v_mul_f32_e32 v53, v84, v53
	v_mul_f32_e32 v58, v84, v59
	v_cvt_pk_bf16_f32 v57, v57, v58
	global_store_dwordx2 v[86:87], v[56:57], off offset:192
	v_cvt_pk_bf16_f32 v52, v52, v53
	v_mul_f32_e32 v53, v84, v54
	v_mul_f32_e32 v54, v84, v55
	v_cvt_pk_bf16_f32 v53, v53, v54
	global_store_dwordx2 v[86:87], v[52:53], off offset:224
	s_and_saveexec_b64 s[14:15], s[40:41]
	s_cbranch_execz .LBB0_403
	s_mov_b32 s0, 0x800000
	v_cmp_gt_f32_e32 vcc, s0, v9
	s_mov_b32 s0, 0x3f317217
	s_lshl_b64 s[38:39], s[38:39], 20
	v_cndmask_b32_e64 v52, 0, 32, vcc
	v_ldexp_f32 v9, v9, v52
	v_log_f32_e32 v9, v9
	v_cndmask_b32_e32 v52, 0, v126, vcc
	v_lshlrev_b64 v[10:11], 6, v[10:11]
	v_mul_f32_e32 v53, 0x3f317217, v9
	v_fma_f32 v53, v9, s0, -v53
	s_mov_b32 s0, 0x7f800000
	v_fmac_f32_e32 v53, 0x3377d1cf, v9
	v_cmp_lt_f32_e64 vcc, |v9|, s0
	v_readlane_b32 s0, v254, 23
	v_fmac_f32_e32 v53, 0x3f317217, v9
	s_add_u32 s38, s0, s38
	v_readlane_b32 s0, v254, 24
	v_cndmask_b32_e32 v9, v9, v53, vcc
	s_addc_u32 s39, s0, s39
	v_sub_f32_e32 v9, v9, v52
	v_lshl_add_u64 v[10:11], s[38:39], 0, v[10:11]
	s_lshl_b32 s0, s89, 2
	v_fmac_f32_e32 v9, 0x3db504f3, v85
	v_lshl_add_u64 v[10:11], v[10:11], 0, s[0:1]
	global_store_dword v[10:11], v9, off
	s_branch .LBB0_403
